# lin_l1/l3 conv taps: prefetch all 4 tap rows per instance in one burst; X1 row-op wave sums via DPP/permlane swaps
# speedup vs baseline: 1.0077x; 1.0008x over previous
; DI void unpack8(const u32x4 w, float (&f)[8]) { f[0] = bflo(w.x); f[1] = bfhi(w.x); f[2] = bflo(w.y); f[3] = bfhi(w.y); f[4] = bflo(w.z); f[5] = bfhi(w.z); f[6] = bflo(w.w); f[7] = bfhi(w.w); }
; template <bool WN, bool WT> DI void load_qk_tile(CArgs& a, int l, int mx, int which, int b, int h, int c, LAS bf16_t* dstN, LAS bf16_t* dstT, int tid) {
;     ...
;         const int dg = tid & 7, r0 = tid >> 3; const int cb = (which ? ZMK : ZMQ) + h * 64 + 8 * dg, cidx = (which ? 256 : 0) + h * 64 + 8 * dg;
;         float wv[4][8], bias[8];
; #pragma unroll
;         for (int kk = 0; kk < 4; ++kk) { const f32x4 w0 = *(const f32x4*)(a.in[I_CONVW] + (size_t)(l * 4 + kk) * 512 + cidx), w1 = *(const f32x4*)(a.in[I_CONVW] + (size_t)(l * 4 + kk) * 512 + cidx + 4);
; #pragma unroll
;             for (int e = 0; e < 4; ++e) { wv[kk][e] = w0[e]; wv[kk][4 + e] = w1[e]; } }
;         { const f32x4 b0 = *(const f32x4*)(a.in[I_CONVB] + l * 512 + cidx), b1 = *(const f32x4*)(a.in[I_CONVB] + l * 512 + cidx + 4);
; #pragma unroll
;             for (int e = 0; e < 4; ++e) { bias[e] = b0[e]; bias[4 + e] = b1[e]; } }
;         const float scl = which ? 1.f : 0.125f;
; #pragma unroll
;         for (int rr = 0; rr < 2; ++rr) { const int r = r0 + 64 * rr; float acc[8];
; #pragma unroll
;             for (int e = 0; e < 8; ++e) acc[e] = bias[e];
; #pragma unroll
;             for (int kk = 0; kk < 4; ++kk) { const int sidx = c * 128 + r - 3 + kk;
;                 if (sidx >= 0) { float v[8]; unpack8(*(const u32x4*)(zb + (t0 + r - 3 + kk) * NZ + cb), v);
; #pragma unroll
;                     for (int e = 0; e < 8; ++e) acc[e] += wv[kk][e] * v[e]; } }
.LBB0_206:
	v_readlane_b32 s0, v253, 19
	v_readlane_b32 s1, v253, 20
	s_load_dwordx4 s[16:19], s[0:1], 0xa0
	v_lshlrev_b32_e32 v0, 3, v114
	v_and_b32_e32 v60, 56, v0
	v_lshl_or_b32 v42, s14, 6, v60
	v_lshlrev_b32_e32 v80, 2, v42
	v_readlane_b32 s0, v253, 17
	s_waitcnt lgkmcnt(0)
	v_lshl_add_u64 v[0:1], s[16:17], 0, v[80:81]
	v_readlane_b32 s1, v253, 18
	v_ashrrev_i32_e32 v46, 3, v114
	v_add_u32_e32 v61, s3, v46
	v_lshl_add_u64 v[8:9], s[0:1], 2, v[0:1]
	v_readlane_b32 s0, v254, 19
	v_readlane_b32 s1, v254, 20
	s_lshl_b64 s[0:1], s[0:1], 2
	s_add_u32 s0, s18, s0
	global_load_dwordx4 v[32:35], v[8:9], off offset:16
	global_load_dwordx4 v[36:39], v[8:9], off
	global_load_dwordx4 v[24:27], v[8:9], off offset:2064
	global_load_dwordx4 v[28:31], v[8:9], off offset:2048
	v_add_co_u32_e32 v12, vcc, s49, v8
	s_addc_u32 s1, s19, s1
	v_lshl_add_u64 v[10:11], v[8:9], 0, s[50:51]
	global_load_dwordx4 v[0:3], v80, s[0:1] offset:16
	global_load_dwordx4 v[4:7], v80, s[0:1]
	v_addc_co_u32_e32 v13, vcc, 0, v9, vcc
	v_lshl_add_u64 v[8:9], v[8:9], 0, s[58:59]
	global_load_dwordx4 v[20:23], v[12:13], off
	global_load_dwordx4 v[16:19], v[10:11], off offset:16
	s_nop 0
	global_load_dwordx4 v[12:15], v[12:13], off offset:2048
	s_nop 0
	global_load_dwordx4 v[8:11], v[8:9], off offset:16
	s_add_u32 s0, s36, -3
	v_ashrrev_i32_e32 v47, 31, v46
	v_lshlrev_b32_e32 v80, 1, v42
	s_addc_u32 s1, 0, -1
	v_cmp_lt_i32_e32 vcc, 2, v61
	v_lshl_add_u64 v[42:43], s[88:89], 0, v[80:81]
	v_lshl_add_u64 v[56:57], s[0:1], 0, v[46:47]
	s_waitcnt vmcnt(5)
	v_mov_b32_e32 v50, v0
	s_waitcnt vmcnt(4)
	v_mov_b32_e32 v54, v4
	v_mov_b32_e32 v55, v5
	v_mov_b32_e32 v52, v6
	v_mov_b32_e32 v53, v7
	v_mov_b32_e32 v51, v1
	v_mov_b32_e32 v48, v2
	v_mov_b32_e32 v49, v3
	v_mad_i64_i32 v[162:163], s[16:17], v56, s55, v[42:43]
	global_load_dwordx4 v[146:149], v[162:163], off offset:1024
	s_mov_b32 s100, 0x1a00
	s_mov_b32 s101, 0
	v_lshl_add_u64 v[162:163], v[162:163], 0, s[100:101]
	global_load_dwordx4 v[150:153], v[162:163], off offset:1024
	v_lshl_add_u64 v[162:163], v[162:163], 0, s[100:101]
	global_load_dwordx4 v[154:157], v[162:163], off offset:1024
	v_lshl_add_u64 v[162:163], v[162:163], 0, s[100:101]
	global_load_dwordx4 v[158:161], v[162:163], off offset:1024
	s_waitcnt vmcnt(0)
	s_and_saveexec_b64 s[4:5], vcc
	s_cbranch_execz .LBB0_210
	v_mov_b32_e32 v48, v146
	v_mov_b32_e32 v49, v147
	v_mov_b32_e32 v50, v148
	v_mov_b32_e32 v51, v149
	v_lshlrev_b32_e32 v52, 16, v48
	v_and_b32_e32 v53, 0xffff0000, v48
	v_lshlrev_b32_e32 v48, 16, v49
	v_and_b32_e32 v49, 0xffff0000, v49
	v_lshlrev_b32_e32 v62, 16, v50
	v_and_b32_e32 v63, 0xffff0000, v50
	v_lshlrev_b32_e32 v64, 16, v51
	v_and_b32_e32 v65, 0xffff0000, v51
	v_pk_fma_f32 v[54:55], v[36:37], v[52:53], v[4:5]
	v_pk_fma_f32 v[52:53], v[38:39], v[48:49], v[6:7]
	v_pk_fma_f32 v[50:51], v[32:33], v[62:63], v[0:1]
	v_pk_fma_f32 v[48:49], v[34:35], v[64:65], v[2:3]
	s_or_b64 exec, exec, s[4:5]
	v_cmp_lt_i32_e32 vcc, 1, v61
	s_and_saveexec_b64 s[4:5], vcc
	s_cbranch_execnz .LBB0_211

; DI void unpack8(const u32x4 w, float (&f)[8]) { f[0] = bflo(w.x); f[1] = bfhi(w.x); f[2] = bflo(w.y); f[3] = bfhi(w.y); f[4] = bflo(w.z); f[5] = bfhi(w.z); f[6] = bflo(w.w); f[7] = bfhi(w.w); }
; template <bool WN, bool WT> DI void load_qk_tile(CArgs& a, int l, int mx, int which, int b, int h, int c, LAS bf16_t* dstN, LAS bf16_t* dstT, int tid) {
;     ...
;             for (int kk = 0; kk < 4; ++kk) { const int sidx = c * 128 + r - 3 + kk;
;                 if (sidx >= 0) { float v[8]; unpack8(*(const u32x4*)(zb + (t0 + r - 3 + kk) * NZ + cb), v);
; #pragma unroll
;                     for (int e = 0; e < 8; ++e) acc[e] += wv[kk][e] * v[e]; } }
.LBB0_209:
	v_mov_b32_e32 v62, v154
	v_mov_b32_e32 v63, v155
	v_mov_b32_e32 v64, v156
	v_mov_b32_e32 v65, v157
	v_lshlrev_b32_e32 v56, 16, v62
	v_and_b32_e32 v57, 0xffff0000, v62
	v_pk_fma_f32 v[54:55], v[20:21], v[56:57], v[54:55]
	v_lshlrev_b32_e32 v56, 16, v63
	v_and_b32_e32 v57, 0xffff0000, v63
	v_pk_fma_f32 v[52:53], v[22:23], v[56:57], v[52:53]
	v_lshlrev_b32_e32 v56, 16, v64
	v_and_b32_e32 v57, 0xffff0000, v64
	v_pk_fma_f32 v[50:51], v[16:17], v[56:57], v[50:51]
	v_lshlrev_b32_e32 v56, 16, v65
	v_and_b32_e32 v57, 0xffff0000, v65
	v_pk_fma_f32 v[48:49], v[18:19], v[56:57], v[48:49]
	s_or_b64 exec, exec, s[4:5]
	v_cmp_lt_i32_e32 vcc, -1, v61
	s_and_saveexec_b64 s[4:5], vcc
	s_cbranch_execnz .LBB0_213
	s_branch .LBB0_214

; DI void unpack8(const u32x4 w, float (&f)[8]) { f[0] = bflo(w.x); f[1] = bfhi(w.x); f[2] = bflo(w.y); f[3] = bfhi(w.y); f[4] = bflo(w.z); f[5] = bfhi(w.z); f[6] = bflo(w.w); f[7] = bfhi(w.w); }
; template <bool WN, bool WT> DI void load_qk_tile(CArgs& a, int l, int mx, int which, int b, int h, int c, LAS bf16_t* dstN, LAS bf16_t* dstT, int tid) {
;     ...
;             for (int kk = 0; kk < 4; ++kk) { const int sidx = c * 128 + r - 3 + kk;
;                 if (sidx >= 0) { float v[8]; unpack8(*(const u32x4*)(zb + (t0 + r - 3 + kk) * NZ + cb), v);
; #pragma unroll
;                     for (int e = 0; e < 8; ++e) acc[e] += wv[kk][e] * v[e]; } }
.LBB0_211:
	v_mov_b32_e32 v62, v150
	v_mov_b32_e32 v63, v151
	v_mov_b32_e32 v64, v152
	v_mov_b32_e32 v65, v153
	v_lshlrev_b32_e32 v66, 16, v62
	v_and_b32_e32 v67, 0xffff0000, v62
	v_lshlrev_b32_e32 v62, 16, v63
	v_and_b32_e32 v63, 0xffff0000, v63
	v_pk_fma_f32 v[52:53], v[30:31], v[62:63], v[52:53]
	v_lshlrev_b32_e32 v62, 16, v64
	v_and_b32_e32 v63, 0xffff0000, v64
	v_pk_fma_f32 v[50:51], v[24:25], v[62:63], v[50:51]
	v_lshlrev_b32_e32 v62, 16, v65
	v_and_b32_e32 v63, 0xffff0000, v65
	v_pk_fma_f32 v[54:55], v[28:29], v[66:67], v[54:55]
	v_pk_fma_f32 v[48:49], v[26:27], v[62:63], v[48:49]
	s_or_b64 exec, exec, s[4:5]
	v_cmp_lt_i32_e32 vcc, 0, v61
	s_and_saveexec_b64 s[4:5], vcc
	s_cbranch_execnz .LBB0_209

; #define LAS __attribute__((address_space(3)))
; DI void unpack8(const u32x4 w, float (&f)[8]) { f[0] = bflo(w.x); f[1] = bfhi(w.x); f[2] = bflo(w.y); f[3] = bfhi(w.y); f[4] = bflo(w.z); f[5] = bfhi(w.z); f[6] = bflo(w.w); f[7] = bfhi(w.w); }
; DI u32x4 pack8f(const float (&f)[8]) { u32x4 w; w.x = pk2(f[0], f[1]); w.y = pk2(f[2], f[3]); w.z = pk2(f[4], f[5]); w.w = pk2(f[6], f[7]); return w; }
; DI float siluf_(float x) { return x * sigmoidf_(x); }
; template <bool WN, bool WT> DI void load_qk_tile(CArgs& a, int l, int mx, int which, int b, int h, int c, LAS bf16_t* dstN, LAS bf16_t* dstT, int tid) {
;     ...
;         for (int rr = 0; rr < 2; ++rr) { const int r = r0 + 64 * rr; float acc[8];
; #pragma unroll
;             for (int e = 0; e < 8; ++e) acc[e] = bias[e];
; #pragma unroll
;             for (int kk = 0; kk < 4; ++kk) { const int sidx = c * 128 + r - 3 + kk;
;                 if (sidx >= 0) { float v[8]; unpack8(*(const u32x4*)(zb + (t0 + r - 3 + kk) * NZ + cb), v);
; #pragma unroll
;                     for (int e = 0; e < 8; ++e) acc[e] += wv[kk][e] * v[e]; } }
; #pragma unroll
;             for (int e = 0; e < 8; ++e) acc[e] = siluf_(acc[e]) * scl;
;             if (WN) *(LAS u32x4*)(dstN + r * 72 + 8 * dg) = pack8f(acc);
.LBB0_213:
	v_add_u32_e32 v47, s36, v46
	v_mov_b32_e32 v62, v158
	v_mov_b32_e32 v63, v159
	v_mov_b32_e32 v64, v160
	v_mov_b32_e32 v65, v161
	v_lshlrev_b32_e32 v56, 16, v62
	v_and_b32_e32 v57, 0xffff0000, v62
	v_pk_fma_f32 v[54:55], v[12:13], v[56:57], v[54:55]
	v_lshlrev_b32_e32 v56, 16, v63
	v_and_b32_e32 v57, 0xffff0000, v63
	v_pk_fma_f32 v[52:53], v[14:15], v[56:57], v[52:53]
	v_lshlrev_b32_e32 v56, 16, v64
	v_and_b32_e32 v57, 0xffff0000, v64
	v_pk_fma_f32 v[50:51], v[8:9], v[56:57], v[50:51]
	v_lshlrev_b32_e32 v56, 16, v65
	v_and_b32_e32 v57, 0xffff0000, v65
	v_pk_fma_f32 v[48:49], v[10:11], v[56:57], v[48:49]
.LBB0_214:
	s_or_b64 exec, exec, s[4:5]
	v_mul_f32_e32 v56, 0xbfb8aa3b, v54
	v_mul_f32_e32 v57, 0xbfb8aa3b, v55
	v_exp_f32_e32 v56, v56
	v_exp_f32_e32 v57, v57
	s_mov_b32 s4, 0x3e000000
	v_lshl_add_u32 v47, v60, 1, 0
	v_add_f32_e32 v56, 1.0, v56
	v_add_f32_e32 v57, 1.0, v57
	v_rcp_f32_e32 v56, v56
	v_rcp_f32_e32 v57, v57
	s_nop 0
	v_pk_mul_f32 v[54:55], v[54:55], v[56:57]
	v_mul_f32_e32 v56, 0xbfb8aa3b, v52
	v_mul_f32_e32 v57, 0xbfb8aa3b, v53
	v_exp_f32_e32 v56, v56
	v_exp_f32_e32 v57, v57
	v_pk_mul_f32 v[54:55], v[54:55], s[4:5] op_sel_hi:[1,0]
	v_add_f32_e32 v56, 1.0, v56
	v_add_f32_e32 v57, 1.0, v57
	v_rcp_f32_e32 v56, v56
	v_rcp_f32_e32 v57, v57
	s_nop 0
	v_pk_mul_f32 v[52:53], v[52:53], v[56:57]
	s_nop 0
	v_pk_mul_f32 v[56:57], v[52:53], s[4:5] op_sel_hi:[1,0]
	v_mul_f32_e32 v52, 0xbfb8aa3b, v50
	v_mul_f32_e32 v53, 0xbfb8aa3b, v51
	v_exp_f32_e32 v52, v52
	v_exp_f32_e32 v53, v53
	v_add_f32_e32 v52, 1.0, v52
	v_add_f32_e32 v53, 1.0, v53
	v_rcp_f32_e32 v52, v52
	v_rcp_f32_e32 v53, v53
	s_nop 0
	v_pk_mul_f32 v[50:51], v[50:51], v[52:53]
	v_mul_f32_e32 v52, 0xbfb8aa3b, v48
	v_mul_f32_e32 v53, 0xbfb8aa3b, v49
	v_exp_f32_e32 v52, v52
	v_exp_f32_e32 v53, v53
	v_pk_mul_f32 v[50:51], v[50:51], s[4:5] op_sel_hi:[1,0]
	v_add_f32_e32 v52, 1.0, v52
	v_add_f32_e32 v53, 1.0, v53
	v_rcp_f32_e32 v52, v52
	v_rcp_f32_e32 v53, v53
	s_nop 0
	v_pk_mul_f32 v[48:49], v[48:49], v[52:53]
	s_nop 0
	v_pk_mul_f32 v[48:49], v[48:49], s[4:5] op_sel_hi:[1,0]
	v_cvt_pk_bf16_f32 v52, v54, v55
	v_cvt_pk_bf16_f32 v55, v48, v49
	v_mul_lo_u32 v48, v46, s34
	v_add_u32_e32 v46, 64, v46
	v_cvt_pk_bf16_f32 v54, v50, v51
	v_add_u32_e32 v50, v47, v48
	v_add_u32_e32 v51, s3, v46
	v_ashrrev_i32_e32 v47, 31, v46
	v_cvt_pk_bf16_f32 v53, v56, v57
	v_lshl_add_u64 v[48:49], s[0:1], 0, v[46:47]
	v_cmp_lt_i32_e32 vcc, 2, v51
	ds_write_b128 v50, v[52:55]
	v_mad_i64_i32 v[162:163], s[4:5], v48, s55, v[42:43]
	global_load_dwordx4 v[146:149], v[162:163], off offset:1024
	s_mov_b32 s100, 0x1a00
	s_mov_b32 s101, 0
	v_lshl_add_u64 v[162:163], v[162:163], 0, s[100:101]
	global_load_dwordx4 v[150:153], v[162:163], off offset:1024
	v_lshl_add_u64 v[162:163], v[162:163], 0, s[100:101]
	global_load_dwordx4 v[154:157], v[162:163], off offset:1024
	v_lshl_add_u64 v[162:163], v[162:163], 0, s[100:101]
	global_load_dwordx4 v[158:161], v[162:163], off offset:1024
	s_waitcnt vmcnt(0)
	s_and_saveexec_b64 s[0:1], vcc
	s_cbranch_execz .LBB0_218
	v_mov_b32_e32 v52, v146
	v_mov_b32_e32 v53, v147
	v_mov_b32_e32 v54, v148
	v_mov_b32_e32 v55, v149
	v_lshlrev_b32_e32 v56, 16, v52
	v_and_b32_e32 v57, 0xffff0000, v52
	v_pk_fma_f32 v[4:5], v[36:37], v[56:57], v[4:5]
	v_lshlrev_b32_e32 v36, 16, v53
	v_and_b32_e32 v37, 0xffff0000, v53
	v_pk_fma_f32 v[6:7], v[38:39], v[36:37], v[6:7]
	v_lshlrev_b32_e32 v36, 16, v54
	v_and_b32_e32 v37, 0xffff0000, v54
	v_pk_fma_f32 v[0:1], v[32:33], v[36:37], v[0:1]
	v_lshlrev_b32_e32 v32, 16, v55
	v_and_b32_e32 v33, 0xffff0000, v55
	v_pk_fma_f32 v[2:3], v[34:35], v[32:33], v[2:3]
	s_or_b64 exec, exec, s[0:1]
	v_cmp_lt_i32_e32 vcc, 1, v51
	s_and_saveexec_b64 s[0:1], vcc
	s_cbranch_execnz .LBB0_219

; DI void unpack8(const u32x4 w, float (&f)[8]) { f[0] = bflo(w.x); f[1] = bfhi(w.x); f[2] = bflo(w.y); f[3] = bfhi(w.y); f[4] = bflo(w.z); f[5] = bfhi(w.z); f[6] = bflo(w.w); f[7] = bfhi(w.w); }
; template <bool WN, bool WT> DI void load_qk_tile(CArgs& a, int l, int mx, int which, int b, int h, int c, LAS bf16_t* dstN, LAS bf16_t* dstT, int tid) {
;     ...
;             for (int kk = 0; kk < 4; ++kk) { const int sidx = c * 128 + r - 3 + kk;
;                 if (sidx >= 0) { float v[8]; unpack8(*(const u32x4*)(zb + (t0 + r - 3 + kk) * NZ + cb), v);
; #pragma unroll
;                     for (int e = 0; e < 8; ++e) acc[e] += wv[kk][e] * v[e]; } }
.LBB0_217:
	v_mov_b32_e32 v24, v154
	v_mov_b32_e32 v25, v155
	v_mov_b32_e32 v26, v156
	v_mov_b32_e32 v27, v157
	v_lshlrev_b32_e32 v28, 16, v24
	v_and_b32_e32 v29, 0xffff0000, v24
	v_pk_fma_f32 v[4:5], v[20:21], v[28:29], v[4:5]
	v_lshlrev_b32_e32 v20, 16, v25
	v_and_b32_e32 v21, 0xffff0000, v25
	v_pk_fma_f32 v[6:7], v[22:23], v[20:21], v[6:7]
	v_lshlrev_b32_e32 v20, 16, v26
	v_and_b32_e32 v21, 0xffff0000, v26
	v_pk_fma_f32 v[0:1], v[16:17], v[20:21], v[0:1]
	v_lshlrev_b32_e32 v16, 16, v27
	v_and_b32_e32 v17, 0xffff0000, v27
	v_pk_fma_f32 v[2:3], v[18:19], v[16:17], v[2:3]
	s_or_b64 exec, exec, s[0:1]
	v_cmp_lt_i32_e32 vcc, -1, v51
	s_and_saveexec_b64 s[0:1], vcc
	s_cbranch_execnz .LBB0_221
	s_branch .LBB0_222

; DI void unpack8(const u32x4 w, float (&f)[8]) { f[0] = bflo(w.x); f[1] = bfhi(w.x); f[2] = bflo(w.y); f[3] = bfhi(w.y); f[4] = bflo(w.z); f[5] = bfhi(w.z); f[6] = bflo(w.w); f[7] = bfhi(w.w); }
; template <bool WN, bool WT> DI void load_qk_tile(CArgs& a, int l, int mx, int which, int b, int h, int c, LAS bf16_t* dstN, LAS bf16_t* dstT, int tid) {
;     ...
;             for (int kk = 0; kk < 4; ++kk) { const int sidx = c * 128 + r - 3 + kk;
;                 if (sidx >= 0) { float v[8]; unpack8(*(const u32x4*)(zb + (t0 + r - 3 + kk) * NZ + cb), v);
; #pragma unroll
;                     for (int e = 0; e < 8; ++e) acc[e] += wv[kk][e] * v[e]; } }
.LBB0_219:
	v_mov_b32_e32 v32, v150
	v_mov_b32_e32 v33, v151
	v_mov_b32_e32 v34, v152
	v_mov_b32_e32 v35, v153
	v_lshlrev_b32_e32 v36, 16, v32
	v_and_b32_e32 v37, 0xffff0000, v32
	v_pk_fma_f32 v[4:5], v[28:29], v[36:37], v[4:5]
	v_lshlrev_b32_e32 v28, 16, v33
	v_and_b32_e32 v29, 0xffff0000, v33
	v_pk_fma_f32 v[6:7], v[30:31], v[28:29], v[6:7]
	v_lshlrev_b32_e32 v28, 16, v34
	v_and_b32_e32 v29, 0xffff0000, v34
	v_pk_fma_f32 v[0:1], v[24:25], v[28:29], v[0:1]
	v_lshlrev_b32_e32 v24, 16, v35
	v_and_b32_e32 v25, 0xffff0000, v35
	v_pk_fma_f32 v[2:3], v[26:27], v[24:25], v[2:3]
	s_or_b64 exec, exec, s[0:1]
	v_cmp_lt_i32_e32 vcc, 0, v51
	s_and_saveexec_b64 s[0:1], vcc
	s_cbranch_execnz .LBB0_217

; DI void unpack8(const u32x4 w, float (&f)[8]) { f[0] = bflo(w.x); f[1] = bfhi(w.x); f[2] = bflo(w.y); f[3] = bfhi(w.y); f[4] = bflo(w.z); f[5] = bfhi(w.z); f[6] = bflo(w.w); f[7] = bfhi(w.w); }
; template <bool WN, bool WT> DI void load_qk_tile(CArgs& a, int l, int mx, int which, int b, int h, int c, LAS bf16_t* dstN, LAS bf16_t* dstT, int tid) {
;     ...
;             for (int kk = 0; kk < 4; ++kk) { const int sidx = c * 128 + r - 3 + kk;
;                 if (sidx >= 0) { float v[8]; unpack8(*(const u32x4*)(zb + (t0 + r - 3 + kk) * NZ + cb), v);
; #pragma unroll
;                     for (int e = 0; e < 8; ++e) acc[e] += wv[kk][e] * v[e]; } }
.LBB0_221:
	s_waitcnt vmcnt(2)
	v_add_u32_e32 v16, s36, v46
	v_mov_b32_e32 v16, v158
	v_mov_b32_e32 v17, v159
	v_mov_b32_e32 v18, v160
	v_mov_b32_e32 v19, v161
	v_lshlrev_b32_e32 v20, 16, v16
	v_and_b32_e32 v21, 0xffff0000, v16
	v_pk_fma_f32 v[4:5], v[12:13], v[20:21], v[4:5]
	v_lshlrev_b32_e32 v12, 16, v17
	v_and_b32_e32 v13, 0xffff0000, v17
	v_pk_fma_f32 v[6:7], v[14:15], v[12:13], v[6:7]
	v_lshlrev_b32_e32 v12, 16, v18
	v_and_b32_e32 v13, 0xffff0000, v18
	v_pk_fma_f32 v[0:1], v[8:9], v[12:13], v[0:1]
	v_lshlrev_b32_e32 v8, 16, v19
	v_and_b32_e32 v9, 0xffff0000, v19
	v_pk_fma_f32 v[2:3], v[10:11], v[8:9], v[2:3]

; DI void unpack8(const u32x4 w, float (&f)[8]) { f[0] = bflo(w.x); f[1] = bfhi(w.x); f[2] = bflo(w.y); f[3] = bfhi(w.y); f[4] = bflo(w.z); f[5] = bfhi(w.z); f[6] = bflo(w.w); f[7] = bfhi(w.w); }
; template <bool WN, bool WT> DI void load_qk_tile(CArgs& a, int l, int mx, int which, int b, int h, int c, LAS bf16_t* dstN, LAS bf16_t* dstT, int tid) {
;     ...
;         const int dg = tid & 7, r0 = tid >> 3; const int cb = (which ? ZMK : ZMQ) + h * 64 + 8 * dg, cidx = (which ? 256 : 0) + h * 64 + 8 * dg;
;         float wv[4][8], bias[8];
; #pragma unroll
;         for (int kk = 0; kk < 4; ++kk) { const f32x4 w0 = *(const f32x4*)(a.in[I_CONVW] + (size_t)(l * 4 + kk) * 512 + cidx), w1 = *(const f32x4*)(a.in[I_CONVW] + (size_t)(l * 4 + kk) * 512 + cidx + 4);
; #pragma unroll
;             for (int e = 0; e < 4; ++e) { wv[kk][e] = w0[e]; wv[kk][4 + e] = w1[e]; } }
;         { const f32x4 b0 = *(const f32x4*)(a.in[I_CONVB] + l * 512 + cidx), b1 = *(const f32x4*)(a.in[I_CONVB] + l * 512 + cidx + 4);
; #pragma unroll
;             for (int e = 0; e < 4; ++e) { bias[e] = b0[e]; bias[4 + e] = b1[e]; } }
;         const float scl = which ? 1.f : 0.125f;
; #pragma unroll
;         for (int rr = 0; rr < 2; ++rr) { const int r = r0 + 64 * rr; float acc[8];
; #pragma unroll
;             for (int e = 0; e < 8; ++e) acc[e] = bias[e];
; #pragma unroll
;             for (int kk = 0; kk < 4; ++kk) { const int sidx = c * 128 + r - 3 + kk;
;                 if (sidx >= 0) { float v[8]; unpack8(*(const u32x4*)(zb + (t0 + r - 3 + kk) * NZ + cb), v);
; #pragma unroll
;                     for (int e = 0; e < 8; ++e) acc[e] += wv[kk][e] * v[e]; } }
.LBB0_224:
	v_readlane_b32 s0, v253, 19
	v_readlane_b32 s1, v253, 20
	s_load_dwordx4 s[16:19], s[0:1], 0xa0
	v_and_b32_e32 v42, 56, v59
	v_lshl_or_b32 v44, s14, 6, v42
	v_lshlrev_b32_e32 v80, 2, v44
	v_readlane_b32 s0, v253, 17
	s_waitcnt lgkmcnt(0)
	v_lshl_add_u64 v[0:1], s[16:17], 0, v[80:81]
	v_readlane_b32 s1, v253, 18
	v_add_u32_e32 v43, s3, v40
	v_ashrrev_i32_e32 v41, 31, v40
	v_lshl_add_u64 v[8:9], s[0:1], 2, v[0:1]
	s_mov_b64 s[0:1], 0x1400
	v_lshl_add_u64 v[10:11], v[8:9], 0, s[0:1]
	v_readlane_b32 s0, v254, 19
	v_readlane_b32 s1, v254, 20
	s_lshl_b64 s[0:1], s[0:1], 2
	s_add_u32 s0, s18, s0
	s_addc_u32 s1, s19, s1
	global_load_dwordx4 v[32:35], v[8:9], off offset:1040
	global_load_dwordx4 v[36:39], v[8:9], off offset:1024
	global_load_dwordx4 v[24:27], v[8:9], off offset:3088
	global_load_dwordx4 v[28:31], v[8:9], off offset:3072
	v_add_co_u32_e32 v12, vcc, s49, v8
	global_load_dwordx4 v[0:3], v80, s[0:1] offset:1040
	global_load_dwordx4 v[4:7], v80, s[0:1] offset:1024
	s_mov_b64 s[0:1], 0x1c00
	v_addc_co_u32_e32 v13, vcc, 0, v9, vcc
	v_lshl_add_u64 v[8:9], v[8:9], 0, s[0:1]
	global_load_dwordx4 v[20:23], v[12:13], off offset:1024
	global_load_dwordx4 v[16:19], v[10:11], off offset:16
	s_nop 0
	global_load_dwordx4 v[12:15], v[12:13], off offset:3072
	s_nop 0
	global_load_dwordx4 v[8:11], v[8:9], off offset:16
	s_add_u32 s0, s36, -3
	v_lshlrev_b32_e32 v80, 1, v44
	s_addc_u32 s1, 0, -1
	v_cmp_lt_i32_e32 vcc, 2, v43
	v_lshl_add_u64 v[44:45], s[88:89], 0, v[80:81]
	v_lshl_add_u64 v[54:55], s[0:1], 0, v[40:41]
	s_waitcnt vmcnt(5)
	v_mov_b32_e32 v48, v0
	s_waitcnt vmcnt(4)
	v_mov_b32_e32 v52, v4
	v_mov_b32_e32 v53, v5
	v_mov_b32_e32 v50, v6
	v_mov_b32_e32 v51, v7
	v_mov_b32_e32 v49, v1
	v_mov_b32_e32 v46, v2
	v_mov_b32_e32 v47, v3
	v_mad_i64_i32 v[162:163], s[12:13], v54, s55, v[44:45]
	global_load_dwordx4 v[146:149], v[162:163], off offset:1536
	s_mov_b32 s100, 0x1a00
	s_mov_b32 s101, 0
	v_lshl_add_u64 v[162:163], v[162:163], 0, s[100:101]
	global_load_dwordx4 v[150:153], v[162:163], off offset:1536
	v_lshl_add_u64 v[162:163], v[162:163], 0, s[100:101]
	global_load_dwordx4 v[154:157], v[162:163], off offset:1536
	v_lshl_add_u64 v[162:163], v[162:163], 0, s[100:101]
	global_load_dwordx4 v[158:161], v[162:163], off offset:1536
	s_waitcnt vmcnt(0)
	s_and_saveexec_b64 s[4:5], vcc
	s_cbranch_execz .LBB0_228
	v_mov_b32_e32 v46, v146
	v_mov_b32_e32 v47, v147
	v_mov_b32_e32 v48, v148
	v_mov_b32_e32 v49, v149
	v_lshlrev_b32_e32 v50, 16, v46
	v_and_b32_e32 v51, 0xffff0000, v46
	v_lshlrev_b32_e32 v46, 16, v47
	v_and_b32_e32 v47, 0xffff0000, v47
	v_lshlrev_b32_e32 v56, 16, v48
	v_and_b32_e32 v57, 0xffff0000, v48
	v_lshlrev_b32_e32 v60, 16, v49
	v_and_b32_e32 v61, 0xffff0000, v49
	v_pk_fma_f32 v[52:53], v[36:37], v[50:51], v[4:5]
	v_pk_fma_f32 v[50:51], v[38:39], v[46:47], v[6:7]
	v_pk_fma_f32 v[48:49], v[32:33], v[56:57], v[0:1]
	v_pk_fma_f32 v[46:47], v[34:35], v[60:61], v[2:3]
	s_or_b64 exec, exec, s[4:5]
	v_cmp_lt_i32_e32 vcc, 1, v43
	s_and_saveexec_b64 s[4:5], vcc
	s_cbranch_execnz .LBB0_229

; DI void unpack8(const u32x4 w, float (&f)[8]) { f[0] = bflo(w.x); f[1] = bfhi(w.x); f[2] = bflo(w.y); f[3] = bfhi(w.y); f[4] = bflo(w.z); f[5] = bfhi(w.z); f[6] = bflo(w.w); f[7] = bfhi(w.w); }
; template <bool WN, bool WT> DI void load_qk_tile(CArgs& a, int l, int mx, int which, int b, int h, int c, LAS bf16_t* dstN, LAS bf16_t* dstT, int tid) {
;     ...
;             for (int kk = 0; kk < 4; ++kk) { const int sidx = c * 128 + r - 3 + kk;
;                 if (sidx >= 0) { float v[8]; unpack8(*(const u32x4*)(zb + (t0 + r - 3 + kk) * NZ + cb), v);
; #pragma unroll
;                     for (int e = 0; e < 8; ++e) acc[e] += wv[kk][e] * v[e]; } }
.LBB0_227:
	v_mov_b32_e32 v54, v154
	v_mov_b32_e32 v55, v155
	v_mov_b32_e32 v56, v156
	v_mov_b32_e32 v57, v157
	v_lshlrev_b32_e32 v60, 16, v54
	v_and_b32_e32 v61, 0xffff0000, v54
	v_lshlrev_b32_e32 v54, 16, v55
	v_and_b32_e32 v55, 0xffff0000, v55
	v_pk_fma_f32 v[50:51], v[22:23], v[54:55], v[50:51]
	v_lshlrev_b32_e32 v54, 16, v56
	v_and_b32_e32 v55, 0xffff0000, v56
	v_pk_fma_f32 v[48:49], v[16:17], v[54:55], v[48:49]
	v_lshlrev_b32_e32 v54, 16, v57
	v_and_b32_e32 v55, 0xffff0000, v57
	v_pk_fma_f32 v[52:53], v[20:21], v[60:61], v[52:53]
	v_pk_fma_f32 v[46:47], v[18:19], v[54:55], v[46:47]
	s_or_b64 exec, exec, s[4:5]
	v_cmp_lt_i32_e32 vcc, -1, v43
	s_and_saveexec_b64 s[4:5], vcc
	s_cbranch_execnz .LBB0_231
	s_branch .LBB0_232

; DI void unpack8(const u32x4 w, float (&f)[8]) { f[0] = bflo(w.x); f[1] = bfhi(w.x); f[2] = bflo(w.y); f[3] = bfhi(w.y); f[4] = bflo(w.z); f[5] = bfhi(w.z); f[6] = bflo(w.w); f[7] = bfhi(w.w); }
; template <bool WN, bool WT> DI void load_qk_tile(CArgs& a, int l, int mx, int which, int b, int h, int c, LAS bf16_t* dstN, LAS bf16_t* dstT, int tid) {
;     ...
;             for (int kk = 0; kk < 4; ++kk) { const int sidx = c * 128 + r - 3 + kk;
;                 if (sidx >= 0) { float v[8]; unpack8(*(const u32x4*)(zb + (t0 + r - 3 + kk) * NZ + cb), v);
; #pragma unroll
;                     for (int e = 0; e < 8; ++e) acc[e] += wv[kk][e] * v[e]; } }
.LBB0_229:
	v_mov_b32_e32 v60, v150
	v_mov_b32_e32 v61, v151
	v_mov_b32_e32 v62, v152
	v_mov_b32_e32 v63, v153
	v_lshlrev_b32_e32 v56, 16, v60
	v_and_b32_e32 v57, 0xffff0000, v60
	v_pk_fma_f32 v[52:53], v[28:29], v[56:57], v[52:53]
	v_lshlrev_b32_e32 v56, 16, v61
	v_and_b32_e32 v57, 0xffff0000, v61
	v_pk_fma_f32 v[50:51], v[30:31], v[56:57], v[50:51]
	v_lshlrev_b32_e32 v56, 16, v62
	v_and_b32_e32 v57, 0xffff0000, v62
	v_pk_fma_f32 v[48:49], v[24:25], v[56:57], v[48:49]
	v_lshlrev_b32_e32 v56, 16, v63
	v_and_b32_e32 v57, 0xffff0000, v63
	v_pk_fma_f32 v[46:47], v[26:27], v[56:57], v[46:47]
	s_or_b64 exec, exec, s[4:5]
	v_cmp_lt_i32_e32 vcc, 0, v43
	s_and_saveexec_b64 s[4:5], vcc
	s_cbranch_execnz .LBB0_227

; #define LAS __attribute__((address_space(3)))
; DI void unpack8(const u32x4 w, float (&f)[8]) { f[0] = bflo(w.x); f[1] = bfhi(w.x); f[2] = bflo(w.y); f[3] = bfhi(w.y); f[4] = bflo(w.z); f[5] = bfhi(w.z); f[6] = bflo(w.w); f[7] = bfhi(w.w); }
; DI u32x4 pack8f(const float (&f)[8]) { u32x4 w; w.x = pk2(f[0], f[1]); w.y = pk2(f[2], f[3]); w.z = pk2(f[4], f[5]); w.w = pk2(f[6], f[7]); return w; }
; DI float siluf_(float x) { return x * sigmoidf_(x); }
; template <bool WN, bool WT> DI void load_qk_tile(CArgs& a, int l, int mx, int which, int b, int h, int c, LAS bf16_t* dstN, LAS bf16_t* dstT, int tid) {
;     ...
;         for (int rr = 0; rr < 2; ++rr) { const int r = r0 + 64 * rr; float acc[8];
; #pragma unroll
;             for (int e = 0; e < 8; ++e) acc[e] = bias[e];
; #pragma unroll
;             for (int kk = 0; kk < 4; ++kk) { const int sidx = c * 128 + r - 3 + kk;
;                 if (sidx >= 0) { float v[8]; unpack8(*(const u32x4*)(zb + (t0 + r - 3 + kk) * NZ + cb), v);
; #pragma unroll
;                     for (int e = 0; e < 8; ++e) acc[e] += wv[kk][e] * v[e]; } }
; #pragma unroll
;             for (int e = 0; e < 8; ++e) acc[e] = siluf_(acc[e]) * scl;
;             if (WN) *(LAS u32x4*)(dstN + r * 72 + 8 * dg) = pack8f(acc);
.LBB0_231:
	v_add_u32_e32 v41, s36, v40
	v_mov_b32_e32 v54, v158
	v_mov_b32_e32 v55, v159
	v_mov_b32_e32 v56, v160
	v_mov_b32_e32 v57, v161
	v_lshlrev_b32_e32 v60, 16, v54
	v_and_b32_e32 v61, 0xffff0000, v54
	v_lshlrev_b32_e32 v54, 16, v55
	v_and_b32_e32 v55, 0xffff0000, v55
	v_pk_fma_f32 v[50:51], v[14:15], v[54:55], v[50:51]
	v_lshlrev_b32_e32 v54, 16, v56
	v_and_b32_e32 v55, 0xffff0000, v56
	v_pk_fma_f32 v[48:49], v[8:9], v[54:55], v[48:49]
	v_lshlrev_b32_e32 v54, 16, v57
	v_and_b32_e32 v55, 0xffff0000, v57
	v_pk_fma_f32 v[52:53], v[12:13], v[60:61], v[52:53]
	v_pk_fma_f32 v[46:47], v[10:11], v[54:55], v[46:47]
.LBB0_232:
	s_or_b64 exec, exec, s[4:5]
	v_mul_f32_e32 v43, 0xbfb8aa3b, v52
	v_exp_f32_e32 v43, v43
	v_lshl_add_u32 v41, v42, 1, 0
	v_add_f32_e32 v43, 1.0, v43
	v_rcp_f32_e32 v54, v43
	v_mul_f32_e32 v43, 0xbfb8aa3b, v53
	v_exp_f32_e32 v43, v43
	s_nop 0
	v_add_f32_e32 v43, 1.0, v43
	v_rcp_f32_e32 v55, v43
	v_mul_f32_e32 v43, 0xbfb8aa3b, v50
	v_exp_f32_e32 v43, v43
	v_pk_mul_f32 v[52:53], v[52:53], v[54:55]
	v_add_f32_e32 v43, 1.0, v43
	v_rcp_f32_e32 v54, v43
	v_mul_f32_e32 v43, 0xbfb8aa3b, v51
	v_exp_f32_e32 v43, v43
	s_nop 0
	v_add_f32_e32 v43, 1.0, v43
	v_rcp_f32_e32 v55, v43
	v_mul_f32_e32 v43, 0xbfb8aa3b, v48
	v_exp_f32_e32 v43, v43
	v_pk_mul_f32 v[50:51], v[50:51], v[54:55]
	v_add_f32_e32 v43, 1.0, v43
	v_rcp_f32_e32 v54, v43
	v_mul_f32_e32 v43, 0xbfb8aa3b, v49
	v_exp_f32_e32 v43, v43
	s_nop 0
	v_add_f32_e32 v43, 1.0, v43
	v_rcp_f32_e32 v55, v43
	v_mul_f32_e32 v43, 0xbfb8aa3b, v46
	v_exp_f32_e32 v43, v43
	v_pk_mul_f32 v[48:49], v[48:49], v[54:55]
	s_nop 0
	v_cvt_pk_bf16_f32 v48, v48, v49
	v_add_f32_e32 v43, 1.0, v43
	v_rcp_f32_e32 v54, v43
	v_mul_f32_e32 v43, 0xbfb8aa3b, v47
	v_exp_f32_e32 v43, v43
	s_nop 0
	v_add_f32_e32 v43, 1.0, v43
	v_rcp_f32_e32 v55, v43
	s_nop 0
	v_pk_mul_f32 v[54:55], v[46:47], v[54:55]
	v_cvt_pk_bf16_f32 v47, v50, v51
	v_mul_lo_u32 v50, v40, s34
	v_cvt_pk_bf16_f32 v46, v52, v53
	v_cvt_pk_bf16_f32 v49, v54, v55
	v_add_u32_e32 v41, v41, v50
	ds_write_b128 v41, v[46:49] offset:18432
	v_add_u32_e32 v46, 64, v40
	v_add_u32_e32 v43, s3, v46
	v_ashrrev_i32_e32 v47, 31, v46
	v_lshl_add_u64 v[48:49], s[0:1], 0, v[46:47]
	v_cmp_lt_i32_e32 vcc, 2, v43
	v_mad_i64_i32 v[162:163], s[4:5], v48, s55, v[44:45]
	global_load_dwordx4 v[146:149], v[162:163], off offset:1536
	s_mov_b32 s100, 0x1a00
	s_mov_b32 s101, 0
	v_lshl_add_u64 v[162:163], v[162:163], 0, s[100:101]
	global_load_dwordx4 v[150:153], v[162:163], off offset:1536
	v_lshl_add_u64 v[162:163], v[162:163], 0, s[100:101]
	global_load_dwordx4 v[154:157], v[162:163], off offset:1536
	v_lshl_add_u64 v[162:163], v[162:163], 0, s[100:101]
	global_load_dwordx4 v[158:161], v[162:163], off offset:1536
	s_waitcnt vmcnt(0)
	s_and_saveexec_b64 s[0:1], vcc
	s_cbranch_execz .LBB0_236
	v_mov_b32_e32 v52, v146
	v_mov_b32_e32 v53, v147
	v_mov_b32_e32 v54, v148
	v_mov_b32_e32 v55, v149
	v_lshlrev_b32_e32 v56, 16, v52
	v_and_b32_e32 v57, 0xffff0000, v52
	v_pk_fma_f32 v[4:5], v[36:37], v[56:57], v[4:5]
	v_lshlrev_b32_e32 v36, 16, v53
	v_and_b32_e32 v37, 0xffff0000, v53
	v_pk_fma_f32 v[6:7], v[38:39], v[36:37], v[6:7]
	v_lshlrev_b32_e32 v36, 16, v54
	v_and_b32_e32 v37, 0xffff0000, v54
	v_pk_fma_f32 v[0:1], v[32:33], v[36:37], v[0:1]
	v_lshlrev_b32_e32 v32, 16, v55
	v_and_b32_e32 v33, 0xffff0000, v55
	v_pk_fma_f32 v[2:3], v[34:35], v[32:33], v[2:3]
	s_or_b64 exec, exec, s[0:1]
	v_cmp_lt_i32_e32 vcc, 1, v43
	s_and_saveexec_b64 s[0:1], vcc
	s_cbranch_execnz .LBB0_237

; DI void unpack8(const u32x4 w, float (&f)[8]) { f[0] = bflo(w.x); f[1] = bfhi(w.x); f[2] = bflo(w.y); f[3] = bfhi(w.y); f[4] = bflo(w.z); f[5] = bfhi(w.z); f[6] = bflo(w.w); f[7] = bfhi(w.w); }
; template <bool WN, bool WT> DI void load_qk_tile(CArgs& a, int l, int mx, int which, int b, int h, int c, LAS bf16_t* dstN, LAS bf16_t* dstT, int tid) {
;     ...
;             for (int kk = 0; kk < 4; ++kk) { const int sidx = c * 128 + r - 3 + kk;
;                 if (sidx >= 0) { float v[8]; unpack8(*(const u32x4*)(zb + (t0 + r - 3 + kk) * NZ + cb), v);
; #pragma unroll
;                     for (int e = 0; e < 8; ++e) acc[e] += wv[kk][e] * v[e]; } }
.LBB0_235:
	v_mov_b32_e32 v24, v154
	v_mov_b32_e32 v25, v155
	v_mov_b32_e32 v26, v156
	v_mov_b32_e32 v27, v157
	v_lshlrev_b32_e32 v28, 16, v24
	v_and_b32_e32 v29, 0xffff0000, v24
	v_pk_fma_f32 v[4:5], v[20:21], v[28:29], v[4:5]
	v_lshlrev_b32_e32 v20, 16, v25
	v_and_b32_e32 v21, 0xffff0000, v25
	v_pk_fma_f32 v[6:7], v[22:23], v[20:21], v[6:7]
	v_lshlrev_b32_e32 v20, 16, v26
	v_and_b32_e32 v21, 0xffff0000, v26
	v_pk_fma_f32 v[0:1], v[16:17], v[20:21], v[0:1]
	v_lshlrev_b32_e32 v16, 16, v27
	v_and_b32_e32 v17, 0xffff0000, v27
	v_pk_fma_f32 v[2:3], v[18:19], v[16:17], v[2:3]
	s_or_b64 exec, exec, s[0:1]
	v_cmp_lt_i32_e32 vcc, -1, v43
	s_and_saveexec_b64 s[0:1], vcc
	s_cbranch_execnz .LBB0_239
	s_branch .LBB0_240

; DI void unpack8(const u32x4 w, float (&f)[8]) { f[0] = bflo(w.x); f[1] = bfhi(w.x); f[2] = bflo(w.y); f[3] = bfhi(w.y); f[4] = bflo(w.z); f[5] = bfhi(w.z); f[6] = bflo(w.w); f[7] = bfhi(w.w); }
; template <bool WN, bool WT> DI void load_qk_tile(CArgs& a, int l, int mx, int which, int b, int h, int c, LAS bf16_t* dstN, LAS bf16_t* dstT, int tid) {
;     ...
;             for (int kk = 0; kk < 4; ++kk) { const int sidx = c * 128 + r - 3 + kk;
;                 if (sidx >= 0) { float v[8]; unpack8(*(const u32x4*)(zb + (t0 + r - 3 + kk) * NZ + cb), v);
; #pragma unroll
;                     for (int e = 0; e < 8; ++e) acc[e] += wv[kk][e] * v[e]; } }
.LBB0_237:
	v_mov_b32_e32 v32, v150
	v_mov_b32_e32 v33, v151
	v_mov_b32_e32 v34, v152
	v_mov_b32_e32 v35, v153
	v_lshlrev_b32_e32 v36, 16, v32
	v_and_b32_e32 v37, 0xffff0000, v32
	v_pk_fma_f32 v[4:5], v[28:29], v[36:37], v[4:5]
	v_lshlrev_b32_e32 v28, 16, v33
	v_and_b32_e32 v29, 0xffff0000, v33
	v_pk_fma_f32 v[6:7], v[30:31], v[28:29], v[6:7]
	v_lshlrev_b32_e32 v28, 16, v34
	v_and_b32_e32 v29, 0xffff0000, v34
	v_pk_fma_f32 v[0:1], v[24:25], v[28:29], v[0:1]
	v_lshlrev_b32_e32 v24, 16, v35
	v_and_b32_e32 v25, 0xffff0000, v35
	v_pk_fma_f32 v[2:3], v[26:27], v[24:25], v[2:3]
	s_or_b64 exec, exec, s[0:1]
	v_cmp_lt_i32_e32 vcc, 0, v43
	s_and_saveexec_b64 s[0:1], vcc
	s_cbranch_execnz .LBB0_235

; DI void unpack8(const u32x4 w, float (&f)[8]) { f[0] = bflo(w.x); f[1] = bfhi(w.x); f[2] = bflo(w.y); f[3] = bfhi(w.y); f[4] = bflo(w.z); f[5] = bfhi(w.z); f[6] = bflo(w.w); f[7] = bfhi(w.w); }
; DI u32x4 pack8f(const float (&f)[8]) { u32x4 w; w.x = pk2(f[0], f[1]); w.y = pk2(f[2], f[3]); w.z = pk2(f[4], f[5]); w.w = pk2(f[6], f[7]); return w; }
; DI float shx(float v, int o, int lane) { return __int_as_float(__builtin_amdgcn_ds_bpermute((lane ^ o) << 2, __float_as_int(v))); }
; DI float wave_sum(float v, int lane) {
; #pragma unroll
;     for (int o = 1; o < 64; o <<= 1) v += shx(v, o, lane);
;     return v;
; }
; __global__ void __launch_bounds__(512, 2) fwd_mega(Args a_unused) {
;     ...
;                 { float f[8]; float ss = 0.f; if (lane < 48) { unpack8(*(const u32x4*)(zr + ZCQ + 8 * lane), f);
; #pragma unroll
;                         for (int e = 0; e < 8; ++e) ss += f[e] * f[e]; }
;                   const float rs = rsqrtf(wave_sum(ss, lane) * (1.f / 384.f) + EPS);
;                   if (lane < 48) { const float* qn = a.in[I_QN] + l * 384 + 8 * lane;
; #pragma unroll
;                       for (int e = 0; e < 8; ++e) f[e] *= rs * qn[e];
;                       *(u32x4*)((bf16_t*)(ws + WS_CQN) + (size_t)row * 384 + 8 * lane) = pack8f(f); } }
.LBB0_433:
	s_or_b64 exec, exec, s[0:1]
	s_nop 1
	v_add_f32_dpp v37, v37, v37 quad_perm:[1,0,3,2] row_mask:0xf bank_mask:0xf
	s_nop 1
	v_add_f32_dpp v37, v37, v37 quad_perm:[2,3,0,1] row_mask:0xf bank_mask:0xf
	s_nop 1
	v_add_f32_dpp v37, v37, v37 row_half_mirror row_mask:0xf bank_mask:0xf
	s_nop 1
	v_add_f32_dpp v37, v37, v37 row_mirror row_mask:0xf bank_mask:0xf
	v_mov_b32_e32 v38, v37
	s_nop 1
	v_permlane16_swap_b32_e32 v38, v37
	s_waitcnt lgkmcnt(0)
	v_add_f32_e32 v38, v37, v38
	v_mov_b32_e32 v39, v38
	s_nop 1
	v_permlane32_swap_b32_e32 v39, v38
	v_lshlrev_b32_e32 v37, 2, v0
	s_and_saveexec_b64 s[0:1], s[6:7]
	s_cbranch_execz .LBB0_435
	s_waitcnt lgkmcnt(0)
	v_add_f32_e32 v38, v38, v39
	v_fmamk_f32 v38, v38, 0x3b2aaaab, v166
	v_cmp_gt_f32_e32 vcc, s64, v38
	v_mul_f32_e32 v39, 0x4b800000, v38
	s_load_dwordx2 s[10:11], s[94:95], 0xc0
	v_cndmask_b32_e32 v38, v38, v39, vcc
	v_rsq_f32_e32 v38, v38
	v_readlane_b32 s12, v254, 25
	v_readlane_b32 s13, v254, 26
	s_waitcnt lgkmcnt(0)
	s_add_u32 s10, s10, s12
	v_mul_f32_e32 v39, 0x45800000, v38
	s_addc_u32 s11, s11, s13
	v_cndmask_b32_e32 v46, v38, v39, vcc
	global_load_dwordx4 v[38:41], v37, s[10:11] offset:16
	global_load_dwordx4 v[42:45], v37, s[10:11]
	s_waitcnt vmcnt(1)
	v_pk_mul_f32 v[38:39], v[46:47], v[38:39] op_sel_hi:[0,1]
	s_waitcnt vmcnt(0)
	v_pk_mul_f32 v[42:43], v[46:47], v[42:43] op_sel_hi:[0,1]
	v_pk_mul_f32 v[16:17], v[16:17], v[42:43]
	v_pk_mul_f32 v[42:43], v[46:47], v[44:45] op_sel_hi:[0,1]
	v_pk_mul_f32 v[20:21], v[20:21], v[38:39]
	v_pk_mul_f32 v[38:39], v[46:47], v[40:41] op_sel_hi:[0,1]
	v_pk_mul_f32 v[18:19], v[18:19], v[42:43]
	v_pk_mul_f32 v[22:23], v[22:23], v[38:39]
	v_cvt_pk_bf16_f32 v38, v16, v17
	v_cvt_pk_bf16_f32 v39, v18, v19
	v_cvt_pk_bf16_f32 v40, v20, v21
	v_cvt_pk_bf16_f32 v41, v22, v23
	v_lshl_add_u64 v[42:43], s[44:45], 0, v[8:9]
	global_store_dwordx4 v[42:43], v[38:41], off

; DI void unpack8(const u32x4 w, float (&f)[8]) { f[0] = bflo(w.x); f[1] = bfhi(w.x); f[2] = bflo(w.y); f[3] = bfhi(w.y); f[4] = bflo(w.z); f[5] = bfhi(w.z); f[6] = bflo(w.w); f[7] = bfhi(w.w); }
; DI u32x4 pack8f(const float (&f)[8]) { u32x4 w; w.x = pk2(f[0], f[1]); w.y = pk2(f[2], f[3]); w.z = pk2(f[4], f[5]); w.w = pk2(f[6], f[7]); return w; }
; __global__ void __launch_bounds__(512, 2) fwd_mega(Args a_unused) {
;     ...
;                 { float f[8]; float ss = 0.f; if (lane < 32) { unpack8(*(const u32x4*)(zr + ZCKV + 8 * lane), f);
; #pragma unroll
;                         for (int e = 0; e < 8; ++e) ss += f[e] * f[e]; }
;                   const float rs = rsqrtf(wave_sum(ss, lane) * (1.f / 256.f) + EPS);
;                   if (lane < 32) { const float* kn = a.in[I_KVN] + l * 256 + 8 * lane;
; #pragma unroll
;                       for (int e = 0; e < 8; ++e) f[e] *= rs * kn[e];
;                       *(u32x4*)((bf16_t*)(ws + WS_CKVN) + (size_t)row * 256 + 8 * lane) = pack8f(f); } }
.LBB0_437:
	s_or_b64 exec, exec, s[0:1]
	s_nop 1
	v_add_f32_dpp v14, v38, v38 quad_perm:[1,0,3,2] row_mask:0xf bank_mask:0xf
	s_nop 1
	v_add_f32_dpp v14, v14, v14 quad_perm:[2,3,0,1] row_mask:0xf bank_mask:0xf
	s_nop 1
	v_add_f32_dpp v14, v14, v14 row_half_mirror row_mask:0xf bank_mask:0xf
	s_nop 1
	v_add_f32_dpp v14, v14, v14 row_mirror row_mask:0xf bank_mask:0xf
	v_mov_b32_e32 v15, v14
	s_nop 1
	v_permlane16_swap_b32_e32 v15, v14
	s_waitcnt lgkmcnt(0)
	v_add_f32_e32 v14, v14, v15
	v_mov_b32_e32 v15, v14
	s_nop 1
	v_permlane32_swap_b32_e32 v15, v14
	s_and_saveexec_b64 s[0:1], s[8:9]
	s_cbranch_execz .LBB0_430
	s_load_dwordx2 s[10:11], s[94:95], 0xc8
	v_readlane_b32 s12, v254, 27
	v_readlane_b32 s13, v254, 28
	s_waitcnt lgkmcnt(0)
	v_add_f32_e32 v14, v14, v15
	v_fmamk_f32 v14, v14, 0x3b800000, v166
	s_add_u32 s10, s10, s12
	s_addc_u32 s11, s11, s13
	global_load_dwordx4 v[38:41], v37, s[10:11] offset:16
	global_load_dwordx4 v[42:45], v37, s[10:11]
	v_cmp_gt_f32_e32 vcc, s64, v14
	v_mul_f32_e32 v15, 0x4b800000, v14
	s_nop 0
	v_cndmask_b32_e32 v14, v14, v15, vcc
	v_rsq_f32_e32 v14, v14
	s_nop 0
	v_mul_f32_e32 v15, 0x45800000, v14
	v_cndmask_b32_e32 v14, v14, v15, vcc
	s_waitcnt vmcnt(1)
	v_pk_mul_f32 v[38:39], v[14:15], v[38:39] op_sel_hi:[0,1]
	s_waitcnt vmcnt(0)
	v_pk_mul_f32 v[42:43], v[14:15], v[42:43] op_sel_hi:[0,1]
	v_pk_mul_f32 v[24:25], v[24:25], v[42:43]
	v_pk_mul_f32 v[42:43], v[14:15], v[44:45] op_sel_hi:[0,1]
	v_pk_mul_f32 v[14:15], v[14:15], v[40:41] op_sel_hi:[0,1]
	v_pk_mul_f32 v[26:27], v[26:27], v[42:43]
	v_pk_mul_f32 v[28:29], v[28:29], v[38:39]
	v_pk_mul_f32 v[30:31], v[30:31], v[14:15]
	v_cvt_pk_bf16_f32 v38, v24, v25
	v_cvt_pk_bf16_f32 v39, v26, v27
	v_cvt_pk_bf16_f32 v40, v28, v29
	v_cvt_pk_bf16_f32 v41, v30, v31
	v_lshl_add_u64 v[14:15], s[44:45], 0, v[6:7]
	global_store_dwordx4 v[14:15], v[38:41], off
	s_branch .LBB0_430

; DI void unpack8(const u32x4 w, float (&f)[8]) { f[0] = bflo(w.x); f[1] = bfhi(w.x); f[2] = bflo(w.y); f[3] = bfhi(w.y); f[4] = bflo(w.z); f[5] = bfhi(w.z); f[6] = bflo(w.w); f[7] = bfhi(w.w); }
; template <bool WN, bool WT> DI void load_qk_tile(CArgs& a, int l, int mx, int which, int b, int h, int c, LAS bf16_t* dstN, LAS bf16_t* dstT, int tid) {
;     ...
;         const int dg = tid & 7, r0 = tid >> 3; const int cb = (which ? ZMK : ZMQ) + h * 64 + 8 * dg, cidx = (which ? 256 : 0) + h * 64 + 8 * dg;
;         float wv[4][8], bias[8];
; #pragma unroll
;         for (int kk = 0; kk < 4; ++kk) { const f32x4 w0 = *(const f32x4*)(a.in[I_CONVW] + (size_t)(l * 4 + kk) * 512 + cidx), w1 = *(const f32x4*)(a.in[I_CONVW] + (size_t)(l * 4 + kk) * 512 + cidx + 4);
; #pragma unroll
;             for (int e = 0; e < 4; ++e) { wv[kk][e] = w0[e]; wv[kk][4 + e] = w1[e]; } }
;         { const f32x4 b0 = *(const f32x4*)(a.in[I_CONVB] + l * 512 + cidx), b1 = *(const f32x4*)(a.in[I_CONVB] + l * 512 + cidx + 4);
; #pragma unroll
;             for (int e = 0; e < 4; ++e) { bias[e] = b0[e]; bias[4 + e] = b1[e]; } }
;         const float scl = which ? 1.f : 0.125f;
; #pragma unroll
;         for (int rr = 0; rr < 2; ++rr) { const int r = r0 + 64 * rr; float acc[8];
; #pragma unroll
;             for (int e = 0; e < 8; ++e) acc[e] = bias[e];
; #pragma unroll
;             for (int kk = 0; kk < 4; ++kk) { const int sidx = c * 128 + r - 3 + kk;
;                 if (sidx >= 0) { float v[8]; unpack8(*(const u32x4*)(zb + (t0 + r - 3 + kk) * NZ + cb), v);
; #pragma unroll
;                     for (int e = 0; e < 8; ++e) acc[e] += wv[kk][e] * v[e]; } }
.LBB0_456:
	s_andn2_b64 vcc, exec, s[0:1]
	s_cbranch_vccnz .LBB0_474
	s_load_dwordx4 s[12:15], s[94:95], 0xa0
	v_and_b32_e32 v73, 56, v34
	v_lshl_or_b32 v77, s4, 6, v73
	v_lshlrev_b32_e32 v80, 2, v77
	s_mov_b64 s[0:1], 0x1400
	s_waitcnt lgkmcnt(0)
	v_lshl_add_u64 v[32:33], s[12:13], 0, v[80:81]
	v_lshl_add_u64 v[40:41], s[92:93], 2, v[32:33]
	v_lshl_add_u64 v[42:43], v[40:41], 0, s[0:1]
	v_readlane_b32 s0, v254, 19
	v_readlane_b32 s1, v254, 20
	s_lshl_b64 s[0:1], s[0:1], 2
	s_add_u32 s0, s14, s0
	s_addc_u32 s1, s15, s1
	global_load_dwordx4 v[64:67], v[40:41], off offset:1040
	global_load_dwordx4 v[68:71], v[40:41], off offset:1024
	global_load_dwordx4 v[56:59], v[40:41], off offset:3088
	global_load_dwordx4 v[60:63], v[40:41], off offset:3072
	v_add_co_u32_e32 v44, vcc, s49, v40
	global_load_dwordx4 v[32:35], v80, s[0:1] offset:1040
	global_load_dwordx4 v[36:39], v80, s[0:1] offset:1024
	s_mov_b64 s[0:1], 0x1c00
	v_addc_co_u32_e32 v45, vcc, 0, v41, vcc
	v_lshl_add_u64 v[40:41], v[40:41], 0, s[0:1]
	global_load_dwordx4 v[52:55], v[44:45], off offset:1024
	global_load_dwordx4 v[48:51], v[42:43], off offset:16
	s_nop 0
	global_load_dwordx4 v[44:47], v[44:45], off offset:3072
	s_nop 0
	global_load_dwordx4 v[40:43], v[40:41], off offset:16
	v_ashrrev_i32_e32 v102, 3, v72
	s_add_u32 s0, s36, -3
	v_add_u32_e32 v75, s10, v102
	v_ashrrev_i32_e32 v103, 31, v102
	v_lshlrev_b32_e32 v80, 1, v77
	s_addc_u32 s1, 0, -1
	v_cmp_lt_i32_e32 vcc, 2, v75
	v_lshl_add_u64 v[100:101], s[88:89], 0, v[80:81]
	v_lshl_add_u64 v[112:113], s[0:1], 0, v[102:103]
	s_waitcnt vmcnt(5)
	v_mov_b32_e32 v106, v32
	s_waitcnt vmcnt(4)
	v_mov_b32_e32 v110, v36
	v_mov_b32_e32 v111, v37
	v_mov_b32_e32 v108, v38
	v_mov_b32_e32 v109, v39
	v_mov_b32_e32 v107, v33
	v_mov_b32_e32 v104, v34
	v_mov_b32_e32 v105, v35
	v_mad_i64_i32 v[162:163], s[12:13], v112, s55, v[100:101]
	global_load_dwordx4 v[146:149], v[162:163], off offset:1536
	s_mov_b32 s100, 0x1a00
	s_mov_b32 s101, 0
	v_lshl_add_u64 v[162:163], v[162:163], 0, s[100:101]
	global_load_dwordx4 v[150:153], v[162:163], off offset:1536
	v_lshl_add_u64 v[162:163], v[162:163], 0, s[100:101]
	global_load_dwordx4 v[154:157], v[162:163], off offset:1536
	v_lshl_add_u64 v[162:163], v[162:163], 0, s[100:101]
	global_load_dwordx4 v[158:161], v[162:163], off offset:1536
	s_waitcnt vmcnt(0)
	s_and_saveexec_b64 s[4:5], vcc
	s_cbranch_execz .LBB0_461
	v_mov_b32_e32 v104, v146
	v_mov_b32_e32 v105, v147
	v_mov_b32_e32 v106, v148
	v_mov_b32_e32 v107, v149
	v_lshlrev_b32_e32 v108, 16, v104
	v_and_b32_e32 v109, 0xffff0000, v104
	v_lshlrev_b32_e32 v104, 16, v105
	v_and_b32_e32 v105, 0xffff0000, v105
	v_lshlrev_b32_e32 v114, 16, v106
	v_and_b32_e32 v115, 0xffff0000, v106
	v_lshlrev_b32_e32 v116, 16, v107
	v_and_b32_e32 v117, 0xffff0000, v107
	v_pk_fma_f32 v[110:111], v[68:69], v[108:109], v[36:37]
	v_pk_fma_f32 v[108:109], v[70:71], v[104:105], v[38:39]
	v_pk_fma_f32 v[106:107], v[64:65], v[114:115], v[32:33]
	v_pk_fma_f32 v[104:105], v[66:67], v[116:117], v[34:35]
	s_or_b64 exec, exec, s[4:5]
	v_cmp_lt_i32_e32 vcc, 1, v75
	s_and_saveexec_b64 s[4:5], vcc
	s_cbranch_execnz .LBB0_462

; DI void unpack8(const u32x4 w, float (&f)[8]) { f[0] = bflo(w.x); f[1] = bfhi(w.x); f[2] = bflo(w.y); f[3] = bfhi(w.y); f[4] = bflo(w.z); f[5] = bfhi(w.z); f[6] = bflo(w.w); f[7] = bfhi(w.w); }
; template <bool WN, bool WT> DI void load_qk_tile(CArgs& a, int l, int mx, int which, int b, int h, int c, LAS bf16_t* dstN, LAS bf16_t* dstT, int tid) {
;     ...
;             for (int kk = 0; kk < 4; ++kk) { const int sidx = c * 128 + r - 3 + kk;
;                 if (sidx >= 0) { float v[8]; unpack8(*(const u32x4*)(zb + (t0 + r - 3 + kk) * NZ + cb), v);
; #pragma unroll
;                     for (int e = 0; e < 8; ++e) acc[e] += wv[kk][e] * v[e]; } }
.LBB0_460:
	v_mov_b32_e32 v112, v154
	v_mov_b32_e32 v113, v155
	v_mov_b32_e32 v114, v156
	v_mov_b32_e32 v115, v157
	v_lshlrev_b32_e32 v116, 16, v112
	v_and_b32_e32 v117, 0xffff0000, v112
	v_lshlrev_b32_e32 v112, 16, v113
	v_and_b32_e32 v113, 0xffff0000, v113
	v_pk_fma_f32 v[108:109], v[54:55], v[112:113], v[108:109]
	v_lshlrev_b32_e32 v112, 16, v114
	v_and_b32_e32 v113, 0xffff0000, v114
	v_pk_fma_f32 v[106:107], v[48:49], v[112:113], v[106:107]
	v_lshlrev_b32_e32 v112, 16, v115
	v_and_b32_e32 v113, 0xffff0000, v115
	v_pk_fma_f32 v[110:111], v[52:53], v[116:117], v[110:111]
	v_pk_fma_f32 v[104:105], v[50:51], v[112:113], v[104:105]
	s_or_b64 exec, exec, s[4:5]
	v_cmp_lt_i32_e32 vcc, -1, v75
	s_and_saveexec_b64 s[4:5], vcc
	s_cbranch_execnz .LBB0_464
	s_branch .LBB0_465

; DI void unpack8(const u32x4 w, float (&f)[8]) { f[0] = bflo(w.x); f[1] = bfhi(w.x); f[2] = bflo(w.y); f[3] = bfhi(w.y); f[4] = bflo(w.z); f[5] = bfhi(w.z); f[6] = bflo(w.w); f[7] = bfhi(w.w); }
; template <bool WN, bool WT> DI void load_qk_tile(CArgs& a, int l, int mx, int which, int b, int h, int c, LAS bf16_t* dstN, LAS bf16_t* dstT, int tid) {
;     ...
;             for (int kk = 0; kk < 4; ++kk) { const int sidx = c * 128 + r - 3 + kk;
;                 if (sidx >= 0) { float v[8]; unpack8(*(const u32x4*)(zb + (t0 + r - 3 + kk) * NZ + cb), v);
; #pragma unroll
;                     for (int e = 0; e < 8; ++e) acc[e] += wv[kk][e] * v[e]; } }
.LBB0_462:
	v_mov_b32_e32 v114, v150
	v_mov_b32_e32 v115, v151
	v_mov_b32_e32 v116, v152
	v_mov_b32_e32 v117, v153
	v_lshlrev_b32_e32 v118, 16, v114
	v_and_b32_e32 v119, 0xffff0000, v114
	v_lshlrev_b32_e32 v114, 16, v115
	v_and_b32_e32 v115, 0xffff0000, v115
	v_pk_fma_f32 v[108:109], v[62:63], v[114:115], v[108:109]
	v_lshlrev_b32_e32 v114, 16, v116
	v_and_b32_e32 v115, 0xffff0000, v116
	v_pk_fma_f32 v[106:107], v[56:57], v[114:115], v[106:107]
	v_lshlrev_b32_e32 v114, 16, v117
	v_and_b32_e32 v115, 0xffff0000, v117
	v_pk_fma_f32 v[110:111], v[60:61], v[118:119], v[110:111]
	v_pk_fma_f32 v[104:105], v[58:59], v[114:115], v[104:105]
	s_or_b64 exec, exec, s[4:5]
	v_cmp_lt_i32_e32 vcc, 0, v75
	s_and_saveexec_b64 s[4:5], vcc
	s_cbranch_execnz .LBB0_460

; #define LAS __attribute__((address_space(3)))
; DI unsigned f2bf(float f) { unsigned u = __builtin_bit_cast(unsigned, f); return (u + 0x7fffu + ((u >> 16) & 1u)) >> 16; }
; DI void unpack8(const u32x4 w, float (&f)[8]) { f[0] = bflo(w.x); f[1] = bfhi(w.x); f[2] = bflo(w.y); f[3] = bfhi(w.y); f[4] = bflo(w.z); f[5] = bfhi(w.z); f[6] = bflo(w.w); f[7] = bfhi(w.w); }
; DI u32x4 pack8f(const float (&f)[8]) { u32x4 w; w.x = pk2(f[0], f[1]); w.y = pk2(f[2], f[3]); w.z = pk2(f[4], f[5]); w.w = pk2(f[6], f[7]); return w; }
; DI float siluf_(float x) { return x * sigmoidf_(x); }
; template <bool WN, bool WT> DI void load_qk_tile(CArgs& a, int l, int mx, int which, int b, int h, int c, LAS bf16_t* dstN, LAS bf16_t* dstT, int tid) {
;     ...
;         for (int rr = 0; rr < 2; ++rr) { const int r = r0 + 64 * rr; float acc[8];
; #pragma unroll
;             for (int e = 0; e < 8; ++e) acc[e] = bias[e];
; #pragma unroll
;             for (int kk = 0; kk < 4; ++kk) { const int sidx = c * 128 + r - 3 + kk;
;                 if (sidx >= 0) { float v[8]; unpack8(*(const u32x4*)(zb + (t0 + r - 3 + kk) * NZ + cb), v);
; #pragma unroll
;                     for (int e = 0; e < 8; ++e) acc[e] += wv[kk][e] * v[e]; } }
; #pragma unroll
;             for (int e = 0; e < 8; ++e) acc[e] = siluf_(acc[e]) * scl;
;             if (WN) *(LAS u32x4*)(dstN + r * 72 + 8 * dg) = pack8f(acc);
;             if (WT) {
; #pragma unroll
;                 for (int e = 0; e < 8; ++e) dstT[(8 * dg + e) * 136 + r] = (bf16_t)f2bf(acc[e]); }
.LBB0_464:
	v_add_u32_e32 v75, s36, v102
	v_mov_b32_e32 v112, v158
	v_mov_b32_e32 v113, v159
	v_mov_b32_e32 v114, v160
	v_mov_b32_e32 v115, v161
	v_lshlrev_b32_e32 v116, 16, v112
	v_and_b32_e32 v117, 0xffff0000, v112
	v_lshlrev_b32_e32 v112, 16, v113
	v_and_b32_e32 v113, 0xffff0000, v113
	v_pk_fma_f32 v[108:109], v[46:47], v[112:113], v[108:109]
	v_lshlrev_b32_e32 v112, 16, v114
	v_and_b32_e32 v113, 0xffff0000, v114
	v_pk_fma_f32 v[106:107], v[40:41], v[112:113], v[106:107]
	v_lshlrev_b32_e32 v112, 16, v115
	v_and_b32_e32 v113, 0xffff0000, v115
	v_pk_fma_f32 v[110:111], v[44:45], v[116:117], v[110:111]
	v_pk_fma_f32 v[104:105], v[42:43], v[112:113], v[104:105]
.LBB0_465:
	s_or_b64 exec, exec, s[4:5]
	v_mul_f32_e32 v75, 0xbfb8aa3b, v110
	v_exp_f32_e32 v75, v75
	s_nop 0
	v_add_f32_e32 v75, 1.0, v75
	v_rcp_f32_e32 v75, v75
	s_nop 0
	v_mul_f32_e32 v77, v110, v75
	v_mul_f32_e32 v75, 0xbfb8aa3b, v111
	v_exp_f32_e32 v75, v75
	s_nop 0
	v_add_f32_e32 v75, 1.0, v75
	v_rcp_f32_e32 v75, v75
	s_nop 0
	v_mul_f32_e32 v79, v111, v75
	v_mul_f32_e32 v75, 0xbfb8aa3b, v108
	v_exp_f32_e32 v75, v75
	s_nop 0
	v_add_f32_e32 v75, 1.0, v75
	v_rcp_f32_e32 v75, v75
	s_nop 0
	v_mul_f32_e32 v80, v108, v75
	v_mul_f32_e32 v75, 0xbfb8aa3b, v109
	v_exp_f32_e32 v75, v75
	s_nop 0
	v_add_f32_e32 v75, 1.0, v75
	v_rcp_f32_e32 v75, v75
	s_nop 0
	v_mul_f32_e32 v99, v109, v75
	v_mul_f32_e32 v75, 0xbfb8aa3b, v106
	v_exp_f32_e32 v75, v75
	s_nop 0
	v_add_f32_e32 v75, 1.0, v75
	v_rcp_f32_e32 v75, v75
	s_nop 0
	v_mul_f32_e32 v103, v106, v75
	v_mul_f32_e32 v75, 0xbfb8aa3b, v107
	v_exp_f32_e32 v75, v75
	s_nop 0
	v_add_f32_e32 v75, 1.0, v75
	v_rcp_f32_e32 v75, v75
	s_nop 0
	v_mul_f32_e32 v106, v107, v75
	v_mul_f32_e32 v75, 0xbfb8aa3b, v104
	v_exp_f32_e32 v75, v75
	v_bfe_u32 v107, v77, 16, 1
	v_add3_u32 v77, v77, v107, s33
	v_add_f32_e32 v75, 1.0, v75
	v_rcp_f32_e32 v75, v75
	s_nop 0
	v_mul_f32_e32 v104, v104, v75
	v_mul_f32_e32 v75, 0xbfb8aa3b, v105
	v_exp_f32_e32 v75, v75
	s_nop 0
	v_add_f32_e32 v75, 1.0, v75
	v_rcp_f32_e32 v75, v75
	s_nop 0
	v_mul_f32_e32 v105, v105, v75
	v_lshl_add_u32 v75, v102, 1, 0
	v_mad_u32_u24 v107, v73, s29, v75
	ds_write_b16_d16_hi v107, v77
	v_bfe_u32 v77, v79, 16, 1
	v_add3_u32 v77, v79, v77, s33
	ds_write_b16_d16_hi v107, v77 offset:272
	v_bfe_u32 v77, v80, 16, 1
	v_add3_u32 v77, v80, v77, s33
	ds_write_b16_d16_hi v107, v77 offset:544
	v_bfe_u32 v77, v99, 16, 1
	v_add3_u32 v77, v99, v77, s33
	ds_write_b16_d16_hi v107, v77 offset:816
	v_bfe_u32 v77, v103, 16, 1
	v_add3_u32 v77, v103, v77, s33
	ds_write_b16_d16_hi v107, v77 offset:1088
	v_bfe_u32 v77, v106, 16, 1
	v_add3_u32 v77, v106, v77, s33
	ds_write_b16_d16_hi v107, v77 offset:1360
	v_bfe_u32 v77, v104, 16, 1
	v_add3_u32 v77, v104, v77, s33
	ds_write_b16_d16_hi v107, v77 offset:1632
	v_bfe_u32 v77, v105, 16, 1
	v_add3_u32 v77, v105, v77, s33
	v_add_u32_e32 v102, 64, v102
	ds_write_b16_d16_hi v107, v77 offset:1904
	v_add_u32_e32 v77, s10, v102
	v_ashrrev_i32_e32 v103, 31, v102
	v_lshl_add_u64 v[104:105], s[0:1], 0, v[102:103]
	v_cmp_lt_i32_e32 vcc, 2, v77
	v_mad_i64_i32 v[162:163], s[4:5], v104, s55, v[100:101]
	global_load_dwordx4 v[146:149], v[162:163], off offset:1536
	s_mov_b32 s100, 0x1a00
	s_mov_b32 s101, 0
	v_lshl_add_u64 v[162:163], v[162:163], 0, s[100:101]
	global_load_dwordx4 v[150:153], v[162:163], off offset:1536
	v_lshl_add_u64 v[162:163], v[162:163], 0, s[100:101]
	global_load_dwordx4 v[154:157], v[162:163], off offset:1536
	v_lshl_add_u64 v[162:163], v[162:163], 0, s[100:101]
	global_load_dwordx4 v[158:161], v[162:163], off offset:1536
	s_waitcnt vmcnt(0)
	s_and_saveexec_b64 s[0:1], vcc
	s_cbranch_execz .LBB0_469
	v_mov_b32_e32 v106, v146
	v_mov_b32_e32 v107, v147
	v_mov_b32_e32 v108, v148
	v_mov_b32_e32 v109, v149
	v_lshlrev_b32_e32 v110, 16, v106
	v_and_b32_e32 v111, 0xffff0000, v106
	v_pk_fma_f32 v[36:37], v[68:69], v[110:111], v[36:37]
	v_lshlrev_b32_e32 v68, 16, v107
	v_and_b32_e32 v69, 0xffff0000, v107
	v_pk_fma_f32 v[38:39], v[70:71], v[68:69], v[38:39]
	v_lshlrev_b32_e32 v68, 16, v108
	v_and_b32_e32 v69, 0xffff0000, v108
	v_pk_fma_f32 v[32:33], v[64:65], v[68:69], v[32:33]
	v_lshlrev_b32_e32 v64, 16, v109
	v_and_b32_e32 v65, 0xffff0000, v109
	v_pk_fma_f32 v[34:35], v[66:67], v[64:65], v[34:35]
	s_or_b64 exec, exec, s[0:1]
	v_cmp_lt_i32_e32 vcc, 1, v77
	s_and_saveexec_b64 s[0:1], vcc
	s_cbranch_execnz .LBB0_470

; DI void unpack8(const u32x4 w, float (&f)[8]) { f[0] = bflo(w.x); f[1] = bfhi(w.x); f[2] = bflo(w.y); f[3] = bfhi(w.y); f[4] = bflo(w.z); f[5] = bfhi(w.z); f[6] = bflo(w.w); f[7] = bfhi(w.w); }
; template <bool WN, bool WT> DI void load_qk_tile(CArgs& a, int l, int mx, int which, int b, int h, int c, LAS bf16_t* dstN, LAS bf16_t* dstT, int tid) {
;     ...
;             for (int kk = 0; kk < 4; ++kk) { const int sidx = c * 128 + r - 3 + kk;
;                 if (sidx >= 0) { float v[8]; unpack8(*(const u32x4*)(zb + (t0 + r - 3 + kk) * NZ + cb), v);
; #pragma unroll
;                     for (int e = 0; e < 8; ++e) acc[e] += wv[kk][e] * v[e]; } }
.LBB0_468:
	v_mov_b32_e32 v56, v154
	v_mov_b32_e32 v57, v155
	v_mov_b32_e32 v58, v156
	v_mov_b32_e32 v59, v157
	v_lshlrev_b32_e32 v60, 16, v56
	v_and_b32_e32 v61, 0xffff0000, v56
	v_pk_fma_f32 v[36:37], v[52:53], v[60:61], v[36:37]
	v_lshlrev_b32_e32 v52, 16, v57
	v_and_b32_e32 v53, 0xffff0000, v57
	v_pk_fma_f32 v[38:39], v[54:55], v[52:53], v[38:39]
	v_lshlrev_b32_e32 v52, 16, v58
	v_and_b32_e32 v53, 0xffff0000, v58
	v_pk_fma_f32 v[32:33], v[48:49], v[52:53], v[32:33]
	v_lshlrev_b32_e32 v48, 16, v59
	v_and_b32_e32 v49, 0xffff0000, v59
	v_pk_fma_f32 v[34:35], v[50:51], v[48:49], v[34:35]
	s_or_b64 exec, exec, s[0:1]
	v_cmp_lt_i32_e32 vcc, -1, v77
	s_and_saveexec_b64 s[0:1], vcc
	s_cbranch_execnz .LBB0_472
	s_branch .LBB0_473

; DI void unpack8(const u32x4 w, float (&f)[8]) { f[0] = bflo(w.x); f[1] = bfhi(w.x); f[2] = bflo(w.y); f[3] = bfhi(w.y); f[4] = bflo(w.z); f[5] = bfhi(w.z); f[6] = bflo(w.w); f[7] = bfhi(w.w); }
; template <bool WN, bool WT> DI void load_qk_tile(CArgs& a, int l, int mx, int which, int b, int h, int c, LAS bf16_t* dstN, LAS bf16_t* dstT, int tid) {
;     ...
;             for (int kk = 0; kk < 4; ++kk) { const int sidx = c * 128 + r - 3 + kk;
;                 if (sidx >= 0) { float v[8]; unpack8(*(const u32x4*)(zb + (t0 + r - 3 + kk) * NZ + cb), v);
; #pragma unroll
;                     for (int e = 0; e < 8; ++e) acc[e] += wv[kk][e] * v[e]; } }
.LBB0_470:
	v_mov_b32_e32 v64, v150
	v_mov_b32_e32 v65, v151
	v_mov_b32_e32 v66, v152
	v_mov_b32_e32 v67, v153
	v_lshlrev_b32_e32 v68, 16, v64
	v_and_b32_e32 v69, 0xffff0000, v64
	v_pk_fma_f32 v[36:37], v[60:61], v[68:69], v[36:37]
	v_lshlrev_b32_e32 v60, 16, v65
	v_and_b32_e32 v61, 0xffff0000, v65
	v_pk_fma_f32 v[38:39], v[62:63], v[60:61], v[38:39]
	v_lshlrev_b32_e32 v60, 16, v66
	v_and_b32_e32 v61, 0xffff0000, v66
	v_pk_fma_f32 v[32:33], v[56:57], v[60:61], v[32:33]
	v_lshlrev_b32_e32 v56, 16, v67
	v_and_b32_e32 v57, 0xffff0000, v67
	v_pk_fma_f32 v[34:35], v[58:59], v[56:57], v[34:35]
	s_or_b64 exec, exec, s[0:1]
	v_cmp_lt_i32_e32 vcc, 0, v77
	s_and_saveexec_b64 s[0:1], vcc
	s_cbranch_execnz .LBB0_468

; DI void unpack8(const u32x4 w, float (&f)[8]) { f[0] = bflo(w.x); f[1] = bfhi(w.x); f[2] = bflo(w.y); f[3] = bfhi(w.y); f[4] = bflo(w.z); f[5] = bfhi(w.z); f[6] = bflo(w.w); f[7] = bfhi(w.w); }
; template <bool WN, bool WT> DI void load_qk_tile(CArgs& a, int l, int mx, int which, int b, int h, int c, LAS bf16_t* dstN, LAS bf16_t* dstT, int tid) {
;     ...
;             for (int kk = 0; kk < 4; ++kk) { const int sidx = c * 128 + r - 3 + kk;
;                 if (sidx >= 0) { float v[8]; unpack8(*(const u32x4*)(zb + (t0 + r - 3 + kk) * NZ + cb), v);
; #pragma unroll
;                     for (int e = 0; e < 8; ++e) acc[e] += wv[kk][e] * v[e]; } }
.LBB0_472:
	s_waitcnt vmcnt(2)
	v_add_u32_e32 v48, s36, v102
	v_mov_b32_e32 v48, v158
	v_mov_b32_e32 v49, v159
	v_mov_b32_e32 v50, v160
	v_mov_b32_e32 v51, v161
	v_lshlrev_b32_e32 v52, 16, v48
	v_and_b32_e32 v53, 0xffff0000, v48
	v_pk_fma_f32 v[36:37], v[44:45], v[52:53], v[36:37]
	v_lshlrev_b32_e32 v44, 16, v49
	v_and_b32_e32 v45, 0xffff0000, v49
	v_pk_fma_f32 v[38:39], v[46:47], v[44:45], v[38:39]
	v_lshlrev_b32_e32 v44, 16, v50
	v_and_b32_e32 v45, 0xffff0000, v50
	v_pk_fma_f32 v[32:33], v[40:41], v[44:45], v[32:33]
	v_lshlrev_b32_e32 v40, 16, v51
	v_and_b32_e32 v41, 0xffff0000, v51
	v_pk_fma_f32 v[34:35], v[42:43], v[40:41], v[34:35]
